# CD recurrent work queue: next-item atomic kept in flight during the current item
# speedup vs baseline: 1.0761x; 1.0058x over previous
; #define LAS __attribute__((address_space(3)))
; #define SEC_BEGIN(id) unsigned long long _sec_t##id = 0; if ((id) == PROBE_SEC) { __builtin_amdgcn_s_barrier(); _sec_t##id = __builtin_amdgcn_s_memrealtime(); }
; __device__ __forceinline__ void phase_cd_rec(const KP kp, const int bid, const int G, int j, int li, LAS unsigned char* lds, int tid0) {
;     ...
;     SEC_BEGIN(11)
;     unsigned* qhead = (unsigned*)(kp.ws() + WS_CTL) + CW_CNT + 64 * li;
;     volatile LAS unsigned* qslot = (volatile LAS unsigned*)(lds + LDS_BYTES - 8);
;     const float* cw = kp.in(23) + (size_t)j * 4 * 1536; const float* cb = kp.in(24) + (size_t)j * 1536; const float* stc = kp.in(6) + (size_t)j * 128 * 3 * 1536;
;     for (;;) {
;         __syncthreads();
;         if (tid0 == 0) qslot[0] = __hip_atomic_fetch_add(qhead, 1u, __ATOMIC_RELAXED, __HIP_MEMORY_SCOPE_AGENT);
;         __syncthreads();
;         const int it = (int)qslot[0];
.LBB0_150:
	s_waitcnt lgkmcnt(0)
	s_add_u32 s50, s46, 0x14000000
	s_addc_u32 s51, s47, 0
	s_add_u32 s52, s46, 0x1f000000
	s_addc_u32 s53, s47, 0
	s_add_u32 s54, s46, 0x21200000
	s_addc_u32 s55, s47, 0
	s_add_u32 s56, s46, 0x23400000
	s_addc_u32 s57, s47, 0
	s_add_u32 s72, s46, 0x25600000
	s_addc_u32 s73, s47, 0
	s_add_u32 s74, s46, 0x2ca00000
	v_readlane_b32 s0, v254, 42
	s_addc_u32 s75, s47, 0
	v_readlane_b32 s1, v254, 43
	s_lshl_b32 s0, s0, 6
	s_ashr_i32 s1, s0, 31
	s_lshl_b64 s[0:1], s[0:1], 2
	s_add_u32 s0, s46, s0
	s_addc_u32 s1, s47, s1
	s_add_u32 s76, s0, 0x8000
	s_addc_u32 s77, s1, 0
	s_load_dwordx4 s[0:3], s[60:61], 0xb8
	s_mul_i32 s4, s63, 0x6000
	s_mul_hi_u32 s5, s62, 0x6000
	s_add_i32 s6, s5, s4
	s_mul_i32 s7, s62, 0x6000
	s_load_dwordx2 s[4:5], s[60:61], 0x30
	s_waitcnt lgkmcnt(0)
	s_add_u32 s78, s0, s7
	s_addc_u32 s79, s1, s6
	s_mul_i32 s0, s63, 0x1800
	s_mul_hi_u32 s1, s62, 0x1800
	s_add_i32 s1, s1, s0
	s_mul_i32 s0, s62, 0x1800
	s_add_u32 s80, s2, s0
	s_addc_u32 s81, s3, s1
	s_mul_i32 s0, s63, 0x240000
	s_mul_hi_u32 s1, s62, 0x240000
	s_lshl_b64 s[82:83], s[62:63], 7
	s_add_i32 s1, s1, s0
	s_mul_i32 s0, s62, 0x240000
	s_add_u32 s84, s4, s0
	s_addc_u32 s85, s5, s1
	v_cmp_eq_u32_e64 s[40:41], 0, v183
	s_lshl_b32 s8, s62, 4
	s_lshl_b64 s[86:87], s[62:63], 14
	s_and_saveexec_b64 s[0:1], s[40:41]
	s_cbranch_execz .Lcdq_init_done
	v_mov_b32_e32 v250, 1
	global_atomic_add v250, v1, v250, s[76:77] sc0
.Lcdq_init_done:
	s_or_b64 exec, exec, s[0:1]
	s_branch .LBB0_154

; __device__ __forceinline__ void phase_cd_rec(const KP kp, const int bid, const int G, int j, int li, LAS unsigned char* lds, int tid0) {
;     ...
;     for (;;) {
;         __syncthreads();
;         if (tid0 == 0) qslot[0] = __hip_atomic_fetch_add(qhead, 1u, __ATOMIC_RELAXED, __HIP_MEMORY_SCOPE_AGENT);
;         __syncthreads();
;         const int it = (int)qslot[0];
.LBB0_154:
	s_waitcnt vmcnt(0)
	s_barrier
	s_and_saveexec_b64 s[0:1], s[40:41]
	s_cbranch_execz .LBB0_158
	v_mov_b32_e32 v2, s34
	s_nop 0
	ds_write_b32 v2, v250
	s_nop 1
	v_mov_b32_e32 v250, 1
	global_atomic_add v250, v1, v250, s[76:77] sc0
